# static s_setprio 1 for waves 4-7 during prompt attention (on top of v13)
# baseline (speedup 1.0000x reference)
; #define SBAR() __builtin_amdgcn_sched_barrier(0)
; __device__ __forceinline__ int v_st(int k, int c) { const int kk = (k & ~0xC) | ((k & 4) << 1) | ((k & 8) >> 1); return ((kk >> 3) * 4 + (c >> 5)) * 512 + ((kk & 7) * 32 + (c & 31)) * 2; }
; __device__ __forceinline__ int v_rd_base(int lane) { return ((lane & 3) << 3) | (((lane >> 2) & 3) << 6) | (((lane >> 4) & 1) << 5) | (((lane >> 5) & 1) << 8); }
; __device__ __forceinline__ int otid() {
;     const unsigned hw = (unsigned)__builtin_amdgcn_s_getreg((5 << 11) | 4) & 63u;
;     int w = ((volatile __attribute__((address_space(3))) int*)((__attribute__((address_space(3))) unsigned char*)g_lds + LDS_WIDTAB))[hw];
;     w = __builtin_amdgcn_readfirstlane(w);
;     int l; asm volatile("v_mbcnt_lo_u32_b32 %0, -1, 0" : "=v"(l)); asm volatile("v_mbcnt_hi_u32_b32 %0, -1, %0" : "+v"(l));
;     return w * 64 + l;
; }
; template <class TIn, class TOut>
; __device__ __forceinline__ void causal_swa_block(const BlockRef<TIn, TOut>& cur, const BlockRef<TIn, TOut>& nxt, int skv, int W, char* lds, Seam<TIn>& S) {
;     ...
;     const int tid = otid(), wid = __builtin_amdgcn_readfirstlane(tid >> 6), lane = tid & 63, r32 = lane & 31, hi = lane >> 5;
;     const int j_lo = swa_jlo(cur.P0, W);
;     int j_hi = (cur.P0 + QB - 1) / KVBLK + 1; if (j_hi > skv / KVBLK) j_hi = skv / KVBLK;
;     const int NT = j_hi - j_lo;
;     const int kbn = swa_jlo(nxt.P0, W) * KVBLK;
;     const int qlo = cur.P0 + wid * QBLK, qm = qlo + r32 - 4 * hi;
;     char* V_lds = lds; char* K_lds = lds + 2 * SHM_V; float* B_lds = (float*)(lds + 2 * SHM_V + 2 * SHM_K + NW * 64 * 4);
;     float* ws = (float*)(lds + 2 * SHM_V + 2 * SHM_K) + wid * 64; float* li_l = ws, * al_l = ws + 32;
;     float m_reg = -1e30f, l_reg = 0; f32x16 o[4] = {};
;     const int sr = tid >> 4, sc = (tid & 15) * 8, vst0 = v_st(sr, sc), vst1 = v_st(32 + sr, sc), kws = KSWZ(sr, sc * 2);
;     const int vb0 = (int)(uintptr_t)V_lds + v_rd_base(lane);
;     const TIn* Kh = cur.K; const TIn* Vh = cur.V; const float* Ch = cur.CB;
;     ...
;     constexpr int NQL = F32 ? 16 : 8;
;     constexpr bool SK = WSKIP && !F32;
;     ...
;     f32x16 pA0, pA1, pB0, pB1; float mnA, mnB, alA, alB; bf16x8 pa0, pa1, pa2, pa3;
;     if constexpr (F32) { VMW(); SWRITE_VF(0); SBAR(); } else { SWRITE_HV(0); SBAR(); }
;     if (NT > 1) { if constexpr (F32) SLOAD_F((const float*)Kh, KBASE(1)); else SLOAD_H(Kh, Vh, Ch, KBASE(1)); }
.LBB0_1237:
	s_getreg_b32 s2, hwreg(HW_REG_HW_ID, 0, 6)
	s_and_b32 s2, s2, 63
	s_lshl_b32 s2, s2, 2
	s_add_i32 s2, s2, 0
	s_add_i32 s2, s2, 0x23e00
	v_mov_b32_e32 v0, s2
	ds_read_b32 v0, v0
	s_add_i32 s2, s57, 0xfffff001
	s_lshr_b32 s2, s2, 6
	v_mbcnt_lo_u32_b32 v218, -1, 0
	s_cmpk_gt_i32 s57, 0xfff
	s_waitcnt lgkmcnt(0)
	v_readfirstlane_b32 s3, v0
	v_mbcnt_hi_u32_b32 v218, -1, v218
	s_cselect_b32 s28, s2, 0
	s_cmp_lt_u32 s3, 4
	s_cbranch_scc1 .Lattn_prio_lo
	s_setprio 1
.Lattn_prio_lo:
	s_ashr_i32 s2, s57, 31
	v_lshl_add_u32 v34, s3, 6, v218
	v_ashrrev_i32_e32 v230, 4, v34
	s_lshr_b32 s2, s2, 26
	v_add_u32_e32 v231, 32, v230
	s_add_i32 s2, s2, s57
	v_and_b32_e32 v2, 0xfffff0, v230
	v_lshlrev_b32_e32 v3, 1, v230
	v_and_b32_e32 v5, 0xfffff0, v231
	v_lshlrev_b32_e32 v6, 1, v231
	s_addk_i32 s2, 0xff
	v_lshlrev_b32_e32 v0, 3, v218
	v_and_or_b32 v2, v3, 8, v2
	v_and_or_b32 v5, v6, 8, v5
	s_ashr_i32 s2, s2, 6
	v_and_b32_e32 v229, 0x78, v0
	v_lshrrev_b32_e32 v3, 1, v230
	v_lshrrev_b32_e32 v2, 1, v2
	v_bfe_u32 v0, v0, 5, 2
	v_and_b32_e32 v4, 3, v230
	v_lshrrev_b32_e32 v5, 1, v5
	s_add_i32 s2, s2, 1
	v_or_b32_e32 v2, v2, v0
	v_and_or_b32 v3, v3, 4, v4
	v_lshlrev_b32_e32 v35, 1, v229
	v_or_b32_e32 v0, v5, v0
	s_cmpk_lt_i32 s57, 0xf01
	v_lshlrev_b32_e32 v2, 9, v2
	v_lshlrev_b32_e32 v3, 6, v3
	v_and_b32_e32 v4, 48, v35
	v_lshlrev_b32_e32 v0, 9, v0
	s_cselect_b32 s56, s2, 64
	v_or3_b32 v2, v2, v3, v4
	v_or3_b32 v0, v0, v3, v4
	v_mov_b32_e32 v228, v234
	v_readfirstlane_b32 s29, v34
	s_sub_i32 s59, s56, s28
	v_add_u32_e32 v237, 0, v2
	v_add_u32_e32 v238, 0, v0
	s_waitcnt vmcnt(0)
	ds_write_b128 v237, v[124:127]
	ds_write_b128 v238, v[112:115]
	s_cmp_gt_i32 s59, 1
	s_cselect_b64 s[4:5], -1, 0
	s_lshl_b32 s68, s28, 6
	v_lshlrev_b32_e32 v0, 5, v218
	s_cmp_lt_i32 s59, 2
	v_and_b32_e32 v219, 32, v0
	s_cbranch_scc1 .LBB0_1239
	s_or_b32 s2, s68, 64
	v_add_u32_e32 v4, s2, v230
	v_add_u32_e32 v0, v4, v219
	v_lshl_add_u64 v[2:3], v[0:1], 2, s[66:67]
	v_lshl_or_b32 v0, v4, 11, v229
	global_load_dword v176, v[2:3], off
	v_lshlrev_b64 v[2:3], 1, v[0:1]
	v_add_u32_e32 v0, s2, v231
	v_lshl_or_b32 v0, v0, 11, v229
	v_lshl_add_u64 v[4:5], s[64:65], 0, v[2:3]
	v_lshlrev_b64 v[6:7], 1, v[0:1]
	v_lshl_add_u64 v[2:3], s[62:63], 0, v[2:3]
	v_lshl_add_u64 v[8:9], s[64:65], 0, v[6:7]
	global_load_dwordx4 v[124:127], v[4:5], off
	global_load_dwordx4 v[112:115], v[8:9], off
	v_lshl_add_u64 v[4:5], s[62:63], 0, v[6:7]
	global_load_dwordx4 v[116:119], v[2:3], off
	global_load_dwordx4 v[120:123], v[4:5], off

;     ...
;     __syncthreads();
;     if (mode != 1) for (int bh = (int)gridDim.x - 1 - (int)blockIdx.x; bh < NBH; bh += gridDim.x) sample_attn(a, j, bh, ldsb, mode == 2);
.LBB0_1413:
	s_setprio 0
	v_mov_b32_e32 v200, 64
	v_xor_b32_e32 v201, 8, v253
	v_readlane_b32 s2, v254, 19
	v_readlane_b32 s3, v254, 20
	s_andn2_b64 vcc, exec, s[2:3]
	s_barrier
	s_cbranch_vccnz .LBB0_1463
	s_lshl_b32 s0, s62, 18
	s_add_u32 s34, s6, 0xee80000
	s_addc_u32 s35, s7, 0
	v_readlane_b32 s36, v254, 56
	v_readlane_b32 s37, v254, 55
	s_branch .LBB0_1416
